# chain phase: state row 0 moved from wave 0 to wave 5 so the sample-stream scan wave has its SIMD to itself
# speedup vs baseline: 1.0059x; 1.0032x over previous
; __device__ __forceinline__ int tidx() { int t = threadIdx.x; asm volatile("" : "+v"(t)); return t; }
; __device__ __forceinline__ int bidx() { int b = blockIdx.x; asm volatile("" : "+s"(b)); return b; }
; __device__ void phase_rwkv_chain(const Ctx& p, int l) {
;     ...
;     const int tid = tidx(); const int wave = __builtin_amdgcn_readfirstlane(tid >> 6), lane = tid & 63;
;     if (wave >= 4) return;
;     for (int it = bidx() * 4 + wave; it < 1024; it += gridDim.x * 4) {
;         const int b = it >> 9, h = (it >> 6) & 7, v = it & 63;
;         const float* pb = P + (size_t)((b * 64) * 8 + h) * 4096 + lane;
;         float* ub = UC + (size_t)((b * 64) * 8 + h) * 4096 + v * 64 + lane;
.LBB0_570:
	s_andn2_b64 vcc, exec, s[0:1]
	s_cbranch_vccnz .LBB0_581
	s_mov_b32 s0, s86
	s_mov_b32 s1, s87
	v_mov_b32_e32 v0, v184
	s_nop 0
	v_readfirstlane_b32 s2, v0
	s_ashr_i32 s6, s2, 6
	s_cmp_eq_u32 s6, 4
	s_cbranch_scc1 .Lsample_entry
	s_cmp_gt_i32 s6, 5
	s_cbranch_scc1 .LBB0_581
	s_cmp_eq_u32 s6, 0
	s_cbranch_scc1 .LBB0_581
	s_cmp_eq_u32 s6, 5
	s_cselect_b32 s6, 0, s6
	s_mov_b32 s7, s90
	s_lshl_b32 s2, s7, 2
	s_add_i32 s2, s2, s6
	s_cmpk_gt_i32 s2, 0x3ff
	s_cbranch_scc1 .LBB0_581
	s_waitcnt lgkmcnt(0)
	s_and_b32 s3, s2, 0xfffffe00
	s_bfe_u32 s4, s2, 0x30006
	s_or_b32 s3, s3, s4
	s_lshl_b32 s3, s3, 14
	s_and_b32 s5, s2, 63
	s_lshl_b32 s5, s5, 8
	s_add_u32 s20, s0, 0x7700000
	s_addc_u32 s21, s1, 0
	s_add_u32 s20, s20, s3
	s_addc_u32 s21, s21, 0
	s_add_u32 s22, s0, 0x8700000
	s_addc_u32 s23, s1, 0
	s_add_u32 s22, s22, s3
	s_addc_u32 s23, s23, 0
	s_add_u32 s22, s22, s5
	s_addc_u32 s23, s23, 0
	s_mov_b64 s[24:25], s[22:23]
	s_and_b64 s[6:7], s[34:35], exec
	s_cselect_b32 s6, 2, 0
	s_lshr_b32 s7, s2, 9
	s_add_i32 s6, s6, s7
	s_lshl_b32 s6, s6, 17
	s_lshl_b32 s4, s4, 14
	s_add_i32 s6, s6, s4
	s_add_i32 s6, s6, s5
	s_add_u32 s6, s6, 0x4407200
	s_add_u32 s12, s84, s6
	s_addc_u32 s13, s85, 0
	v_and_b32_e32 v254, 63, v184
	v_lshlrev_b32_e32 v248, 4, v254
	v_add_u32_e32 v249, 0x1000, v248
	v_add_u32_e32 v250, 0x2000, v248
	v_add_u32_e32 v251, 0x3000, v248
	v_and_b32_e32 v255, 15, v254
	v_lshrrev_b32_e32 v254, 4, v254
	v_lshlrev_b32_e32 v255, 4, v255
	v_lshl_add_u32 v252, v254, 2, v255
	v_mov_b32_e32 v253, 0
	global_load_dwordx4 v[0:3], v248, s[20:21]
	global_load_dwordx4 v[4:7], v248, s[20:21] offset:1024
	global_load_dwordx4 v[8:11], v248, s[20:21] offset:2048
	global_load_dwordx4 v[12:15], v248, s[20:21] offset:3072
	global_load_dwordx4 v[16:19], v249, s[20:21]
	global_load_dwordx4 v[20:23], v249, s[20:21] offset:1024
	global_load_dwordx4 v[24:27], v249, s[20:21] offset:2048
	global_load_dwordx4 v[28:31], v249, s[20:21] offset:3072
	global_load_dwordx4 v[32:35], v250, s[20:21]
	global_load_dwordx4 v[36:39], v250, s[20:21] offset:1024
	global_load_dwordx4 v[40:43], v250, s[20:21] offset:2048
	global_load_dwordx4 v[44:47], v250, s[20:21] offset:3072
	global_load_dwordx4 v[48:51], v251, s[20:21]
	global_load_dwordx4 v[52:55], v251, s[20:21] offset:1024
	global_load_dwordx4 v[56:59], v251, s[20:21] offset:2048
	global_load_dwordx4 v[60:63], v251, s[20:21] offset:3072
	global_load_dword v236, v252, s[24:25]
	s_add_u32 s20, s20, 0x20000
	s_addc_u32 s21, s21, 0
	s_add_u32 s24, s24, 0x20000
	s_addc_u32 s25, s25, 0
	global_load_dwordx4 v[64:67], v248, s[20:21]
	global_load_dwordx4 v[68:71], v248, s[20:21] offset:1024
	global_load_dwordx4 v[72:75], v248, s[20:21] offset:2048
	global_load_dwordx4 v[76:79], v248, s[20:21] offset:3072
	global_load_dwordx4 v[80:83], v249, s[20:21]
	global_load_dwordx4 v[84:87], v249, s[20:21] offset:1024
	global_load_dwordx4 v[88:91], v249, s[20:21] offset:2048
	global_load_dwordx4 v[92:95], v249, s[20:21] offset:3072
	global_load_dwordx4 v[96:99], v250, s[20:21]
	global_load_dwordx4 v[100:103], v250, s[20:21] offset:1024
	global_load_dwordx4 v[104:107], v250, s[20:21] offset:2048
	global_load_dwordx4 v[108:111], v250, s[20:21] offset:3072
	global_load_dwordx4 v[112:115], v251, s[20:21]
	global_load_dwordx4 v[116:119], v251, s[20:21] offset:1024
	global_load_dwordx4 v[120:123], v251, s[20:21] offset:2048
	global_load_dwordx4 v[124:127], v251, s[20:21] offset:3072
	global_load_dword v237, v252, s[24:25]
	s_add_u32 s20, s20, 0x20000
	s_addc_u32 s21, s21, 0
	s_add_u32 s24, s24, 0x20000
	s_addc_u32 s25, s25, 0
	global_load_dwordx4 v[148:151], v248, s[20:21]
	global_load_dwordx4 v[152:155], v248, s[20:21] offset:1024
	global_load_dwordx4 v[156:159], v248, s[20:21] offset:2048
	global_load_dwordx4 v[160:163], v248, s[20:21] offset:3072
	global_load_dwordx4 v[164:167], v249, s[20:21]
	global_load_dwordx4 v[168:171], v249, s[20:21] offset:1024
	global_load_dwordx4 v[172:175], v249, s[20:21] offset:2048
	global_load_dwordx4 v[176:179], v249, s[20:21] offset:3072
	global_load_dwordx4 v[180:183], v250, s[20:21]
	global_load_dwordx4 v[192:195], v250, s[20:21] offset:1024
	global_load_dwordx4 v[196:199], v250, s[20:21] offset:2048
	global_load_dwordx4 v[200:203], v250, s[20:21] offset:3072
	global_load_dwordx4 v[204:207], v251, s[20:21]
	global_load_dwordx4 v[208:211], v251, s[20:21] offset:1024
	global_load_dwordx4 v[212:215], v251, s[20:21] offset:2048
	global_load_dwordx4 v[216:219], v251, s[20:21] offset:3072
	global_load_dword v238, v252, s[24:25]
	s_add_u32 s20, s20, 0x20000
	s_addc_u32 s21, s21, 0
	s_add_u32 s24, s24, 0x20000
	s_addc_u32 s25, s25, 0
	s_mov_b32 s26, 0
